# NSA phase block-to-workgroup table refitted with the slack measured under the previous table
# speedup vs baseline: 1.0076x; 1.0004x over previous
.LBB0_1247:
	s_or_b64 exec, exec, s[10:11]
	v_lshlrev_b32_e32 v2, 10, v2
	s_add_i32 s62, 0, 0x1fc00
	v_lshlrev_b32_e32 v5, 2, v1
	v_add3_u32 v2, s62, v2, v5
	s_mov_b32 s27, 0
	ds_write_b32 v2, v4
	v_cmp_gt_u32_e32 vcc, 49, v1
	v_mov_b32_e32 v4, 0x1f0
	s_and_saveexec_b64 s[10:11], vcc
	v_cmp_lt_u32_e32 vcc, 2, v1
	s_nop 1
	v_cndmask_b32_e64 v4, 26, 27, vcc
	v_cmp_lt_u32_e32 vcc, 12, v1
	s_nop 1
	v_addc_co_u32_e32 v4, vcc, 0, v4, vcc
	v_cmp_lt_u32_e32 vcc, 22, v1
	s_nop 1
	v_cndmask_b32_e64 v5, 0, 1, vcc
	v_cmp_lt_u32_e32 vcc, 34, v1
	s_nop 1
	v_addc_co_u32_e32 v1, vcc, v4, v5, vcc
	v_lshlrev_b32_e32 v4, 4, v1
	s_or_b64 exec, exec, s[10:11]
	v_add_u32_e32 v4, v4, v3
	v_ashrrev_i32_e32 v5, 31, v4
	v_lshl_add_u64 v[4:5], v[4:5], 2, s[6:7]
	global_load_dword v1, v[4:5], off
	s_ashr_i32 s64, s14, 6
	s_mul_i32 s12, s64, 0x220
	s_mul_i32 s13, s64, 0x440
	s_and_b32 s63, s3, 31
	s_lshl_b32 s4, s3, 6
	s_mov_b32 s3, s27
	s_ashr_i32 s9, s8, 31
	s_add_i32 s86, s12, 0
	s_add_i32 s87, s13, 0
	s_xor_b32 s81, s63, 63
	s_or_b32 s82, s63, 64
	s_xor_b32 s83, s63, 0x7f
	s_lshl_b32 s84, s64, 3
	s_and_b32 s85, s4, 0xffffe000
	s_lshl_b64 s[38:39], s[2:3], 16
	s_lshl_b32 s3, s64, 5
	s_lshl_b64 s[4:5], s[8:9], 19
	s_lshl_b64 s[10:11], s[8:9], 20
	s_add_i32 s86, s86, 0x1b800
	s_add_i32 s87, s87, 0x1c900
	s_add_u32 s88, s10, 0x6e00000
	v_and_b32_e32 v3, 32, v0
	s_addc_u32 s89, s11, 0
	s_lshl_b64 s[40:41], s[8:9], 16
	s_lshl_b32 s8, s64, 12
	s_mov_b32 s28, 0x3fb8aa3b
	v_mov_b32_e32 v195, 0
	s_mov_b32 s65, 0xd000000
	s_movk_i32 s66, 0x90
	s_mov_b64 s[30:31], 0x8000000
	s_brev_b32 s67, 16
	s_mov_b32 s68, 0xff800000
	s_movk_i32 s69, 0x2000
	s_movk_i32 s71, 0x3000
	s_movk_i32 s76, 0x200
	s_mov_b64 s[34:35], 0x2000
	s_mov_b64 s[36:37], 0x4a00000
	s_mov_b32 s77, 0x4a00000
	s_movk_i32 s78, 0x104
	v_mov_b32_e32 v217, 0xff
	s_movk_i32 s79, 0xff
	s_mov_b32 s80, 0x48800000
	v_mov_b32_e32 v218, 1
	v_mov_b32_e32 v219, 0xff800000
	v_cmp_eq_u32_e64 s[6:7], 0, v3
	s_sub_i32 s90, s84, 31
	s_add_i32 s91, 0, 0x12800
	s_lshl_b64 s[42:43], s[4:5], 1
	s_add_i32 s92, 0, 0x1f000
	s_add_i32 s93, 0, 0x10c00
	s_add_i32 s94, s8, 0
	v_mov_b32_e32 v220, 0x7f
	v_mov_b32_e32 v221, 0x42c80001
	v_mov_b32_e32 v222, 0x3fb8aa3b
	s_mov_b32 s95, 0
	s_waitcnt vmcnt(0)
	v_mul_f32_e32 v1, 0x3fb8aa3b, v1
	ds_write_b32 v2, v1 offset:512
	s_waitcnt lgkmcnt(0)
	s_barrier
	s_mov_b32 s4, 0x7a725a00
	v_writelane_b32 v251, s4, 0
	s_mov_b32 s4, 0x7f6b5501
	v_writelane_b32 v251, s4, 1
	s_mov_b32 s4, 0x7d7b4002
	v_writelane_b32 v251, s4, 2
	s_mov_b32 s4, 0x7c783d03
	v_writelane_b32 v251, s4, 3
	s_mov_b32 s4, 0x7e674504
	v_writelane_b32 v251, s4, 4
	s_mov_b32 s4, 0x77634905
	v_writelane_b32 v251, s4, 5
	s_mov_b32 s4, 0x76683e06
	v_writelane_b32 v251, s4, 6
	s_mov_b32 s4, 0x71653f07
	v_writelane_b32 v251, s4, 7
	s_mov_b32 s4, 0x74574308
	v_writelane_b32 v251, s4, 8
	s_mov_b32 s4, 0x734d4609
	v_writelane_b32 v251, s4, 9
	s_mov_b32 s4, 0x6e59380a
	v_writelane_b32 v251, s4, 10
	s_mov_b32 s4, 0x705e2b0b
	v_writelane_b32 v251, s4, 11
	s_mov_b32 s4, 0x6656360c
	v_writelane_b32 v251, s4, 12
	s_mov_b32 s4, 0x615d2d0d
	v_writelane_b32 v251, s4, 13
	s_mov_b32 s4, 0x6460200e
	v_writelane_b32 v251, s4, 14
	s_mov_b32 s4, 0x754c1c0f
	v_writelane_b32 v251, s4, 15
	s_mov_b32 s4, 0x4e483518
	v_writelane_b32 v251, s4, 16
	s_mov_b32 s4, 0x53502f12
	v_writelane_b32 v251, s4, 17
	s_mov_b32 s4, 0x584a231e
	v_writelane_b32 v251, s4, 18
	s_mov_b32 s4, 0x51472e1d
	v_writelane_b32 v251, s4, 19
	s_mov_b32 s4, 0x6a2c2726
	v_writelane_b32 v251, s4, 20
	s_mov_b32 s4, 0x6c343013
	v_writelane_b32 v251, s4, 21
	s_mov_b32 s4, 0x6d292825
	v_writelane_b32 v251, s4, 22
	s_mov_b32 s4, 0x6f312a19
	v_writelane_b32 v251, s4, 23
	s_mov_b32 s4, 0x543b3a1a
	v_writelane_b32 v251, s4, 24
	s_mov_b32 s4, 0x5b413711
	v_writelane_b32 v251, s4, 25
	s_mov_b32 s4, 0x625c1510
	v_writelane_b32 v251, s4, 26
	s_mov_b32 s4, 0x523c3322
	v_writelane_b32 v251, s4, 27
	s_mov_b32 s4, 0x69441f17
	v_writelane_b32 v251, s4, 28
	s_mov_b32 s4, 0x5f4f2114
	v_writelane_b32 v251, s4, 29
	s_mov_b32 s4, 0x4b423224
	v_writelane_b32 v251, s4, 30
	s_mov_b32 s4, 0x79391b16
	v_writelane_b32 v251, s4, 31
	s_branch .LBB0_1252
